# forward-substitution w results: quad transpose in registers, 8-byte stores instead of 2-byte stores
# speedup vs baseline: 1.0100x; 1.0028x over previous
; __device__ __forceinline__ bf16_t f2bf(float x) { return (bf16_t)(pk2(x, 0.f) & 0xffffu); }
; __device__ __forceinline__ void phase_chunk_prep(const Params& p, LAS unsigned char* lds, int wave_s) {
;     ...
;             if (col < 128) {
; #pragma unroll
;                 for (int mm = 0; mm < 4; ++mm)
; #pragma unroll
;                     for (int q4 = 0; q4 < 4; ++q4)
;                         *(f32x4*)(U + ((((col >> 4) * 4 + mm) * 64 + q4 * 16 + (col & 15)) << 2)) = (f32x4){sol[16 * mm + 4 * q4], sol[16 * mm + 4 * q4 + 1], sol[16 * mm + 4 * q4 + 2], sol[16 * mm + 4 * q4 + 3]};
;             } else {
; #pragma unroll
;                 for (int i = 0; i < 64; ++i) img[IMG_WD + i * SWD + (col - 128)] = f2bf(sol[i]);
;             }
.Lfm_w:
	s_mov_b32 s86, 0xaaaaaaaa
	s_mov_b32 s87, 0xaaaaaaaa
	s_mov_b32 s88, 0xcccccccc
	s_mov_b32 s89, 0xcccccccc
	s_sub_i32 s85, s84, 4
	s_lshl_b32 s85, s85, 6
	v_and_b32_e32 v92, 3, v32
	v_lshl_add_u32 v91, v34, 2, v92
	v_mul_u32_u24_e32 v91, 0x108, v91
	v_bfe_u32 v92, v32, 2, 2
	v_lshl_add_u32 v91, v92, 3, v91
	v_add_u32_e32 v91, s85, v91
	v_cndmask_b32_e64 v100, v37, v36, s[86:87]
	v_cndmask_b32_e64 v101, v41, v40, s[86:87]
	v_cndmask_b32_e64 v102, v45, v44, s[86:87]
	v_cndmask_b32_e64 v103, v49, v48, s[86:87]
	v_cndmask_b32_e64 v104, v39, v38, s[86:87]
	v_cndmask_b32_e64 v105, v43, v42, s[86:87]
	v_cndmask_b32_e64 v106, v47, v46, s[86:87]
	v_cndmask_b32_e64 v107, v51, v50, s[86:87]
	v_mov_b32_dpp v108, v100 quad_perm:[1,0,3,2] row_mask:0xf bank_mask:0xf
	v_mov_b32_dpp v109, v101 quad_perm:[1,0,3,2] row_mask:0xf bank_mask:0xf
	v_mov_b32_dpp v110, v102 quad_perm:[1,0,3,2] row_mask:0xf bank_mask:0xf
	v_mov_b32_dpp v111, v103 quad_perm:[1,0,3,2] row_mask:0xf bank_mask:0xf
	v_mov_b32_dpp v112, v104 quad_perm:[1,0,3,2] row_mask:0xf bank_mask:0xf
	v_mov_b32_dpp v113, v105 quad_perm:[1,0,3,2] row_mask:0xf bank_mask:0xf
	v_mov_b32_dpp v114, v106 quad_perm:[1,0,3,2] row_mask:0xf bank_mask:0xf
	v_mov_b32_dpp v115, v107 quad_perm:[1,0,3,2] row_mask:0xf bank_mask:0xf
	v_cndmask_b32_e64 v36, v36, v108, s[86:87]
	v_cndmask_b32_e64 v37, v108, v37, s[86:87]
	v_cndmask_b32_e64 v40, v40, v109, s[86:87]
	v_cndmask_b32_e64 v41, v109, v41, s[86:87]
	v_cndmask_b32_e64 v44, v44, v110, s[86:87]
	v_cndmask_b32_e64 v45, v110, v45, s[86:87]
	v_cndmask_b32_e64 v48, v48, v111, s[86:87]
	v_cndmask_b32_e64 v49, v111, v49, s[86:87]
	v_cndmask_b32_e64 v38, v38, v112, s[86:87]
	v_cndmask_b32_e64 v39, v112, v39, s[86:87]
	v_cndmask_b32_e64 v42, v42, v113, s[86:87]
	v_cndmask_b32_e64 v43, v113, v43, s[86:87]
	v_cndmask_b32_e64 v46, v46, v114, s[86:87]
	v_cndmask_b32_e64 v47, v114, v47, s[86:87]
	v_cndmask_b32_e64 v50, v50, v115, s[86:87]
	v_cndmask_b32_e64 v51, v115, v51, s[86:87]
	v_cndmask_b32_e64 v100, v38, v36, s[88:89]
	v_cndmask_b32_e64 v101, v42, v40, s[88:89]
	v_cndmask_b32_e64 v102, v46, v44, s[88:89]
	v_cndmask_b32_e64 v103, v50, v48, s[88:89]
	v_cndmask_b32_e64 v104, v39, v37, s[88:89]
	v_cndmask_b32_e64 v105, v43, v41, s[88:89]
	v_cndmask_b32_e64 v106, v47, v45, s[88:89]
	v_cndmask_b32_e64 v107, v51, v49, s[88:89]
	v_mov_b32_dpp v108, v100 quad_perm:[2,3,0,1] row_mask:0xf bank_mask:0xf
	v_mov_b32_dpp v109, v101 quad_perm:[2,3,0,1] row_mask:0xf bank_mask:0xf
	v_mov_b32_dpp v110, v102 quad_perm:[2,3,0,1] row_mask:0xf bank_mask:0xf
	v_mov_b32_dpp v111, v103 quad_perm:[2,3,0,1] row_mask:0xf bank_mask:0xf
	v_mov_b32_dpp v112, v104 quad_perm:[2,3,0,1] row_mask:0xf bank_mask:0xf
	v_mov_b32_dpp v113, v105 quad_perm:[2,3,0,1] row_mask:0xf bank_mask:0xf
	v_mov_b32_dpp v114, v106 quad_perm:[2,3,0,1] row_mask:0xf bank_mask:0xf
	v_mov_b32_dpp v115, v107 quad_perm:[2,3,0,1] row_mask:0xf bank_mask:0xf
	v_cndmask_b32_e64 v36, v36, v108, s[88:89]
	v_cndmask_b32_e64 v38, v108, v38, s[88:89]
	v_cndmask_b32_e64 v40, v40, v109, s[88:89]
	v_cndmask_b32_e64 v42, v109, v42, s[88:89]
	v_cndmask_b32_e64 v44, v44, v110, s[88:89]
	v_cndmask_b32_e64 v46, v110, v46, s[88:89]
	v_cndmask_b32_e64 v48, v48, v111, s[88:89]
	v_cndmask_b32_e64 v50, v111, v50, s[88:89]
	v_cndmask_b32_e64 v37, v37, v112, s[88:89]
	v_cndmask_b32_e64 v39, v112, v39, s[88:89]
	v_cndmask_b32_e64 v41, v41, v113, s[88:89]
	v_cndmask_b32_e64 v43, v113, v43, s[88:89]
	v_cndmask_b32_e64 v45, v45, v114, s[88:89]
	v_cndmask_b32_e64 v47, v114, v47, s[88:89]
	v_cndmask_b32_e64 v49, v49, v115, s[88:89]
	v_cndmask_b32_e64 v51, v115, v51, s[88:89]
	v_cndmask_b32_e64 v100, v69, v68, s[86:87]
	v_cndmask_b32_e64 v101, v73, v72, s[86:87]
	v_cndmask_b32_e64 v102, v77, v76, s[86:87]
	v_cndmask_b32_e64 v103, v81, v80, s[86:87]
	v_cndmask_b32_e64 v104, v71, v70, s[86:87]
	v_cndmask_b32_e64 v105, v75, v74, s[86:87]
	v_cndmask_b32_e64 v106, v79, v78, s[86:87]
	v_cndmask_b32_e64 v107, v83, v82, s[86:87]
	v_mov_b32_dpp v108, v100 quad_perm:[1,0,3,2] row_mask:0xf bank_mask:0xf
; __device__ __forceinline__ bf16_t f2bf(float x) { return (bf16_t)(pk2(x, 0.f) & 0xffffu); }
; __device__ __forceinline__ void phase_chunk_prep(const Params& p, LAS unsigned char* lds, int wave_s) {
;     ...
;             } else {
; #pragma unroll
;                 for (int i = 0; i < 64; ++i) img[IMG_WD + i * SWD + (col - 128)] = f2bf(sol[i]);
;             }
	v_mov_b32_dpp v109, v101 quad_perm:[1,0,3,2] row_mask:0xf bank_mask:0xf
	v_mov_b32_dpp v110, v102 quad_perm:[1,0,3,2] row_mask:0xf bank_mask:0xf
	v_mov_b32_dpp v111, v103 quad_perm:[1,0,3,2] row_mask:0xf bank_mask:0xf
	v_mov_b32_dpp v112, v104 quad_perm:[1,0,3,2] row_mask:0xf bank_mask:0xf
	v_mov_b32_dpp v113, v105 quad_perm:[1,0,3,2] row_mask:0xf bank_mask:0xf
	v_mov_b32_dpp v114, v106 quad_perm:[1,0,3,2] row_mask:0xf bank_mask:0xf
	v_mov_b32_dpp v115, v107 quad_perm:[1,0,3,2] row_mask:0xf bank_mask:0xf
	v_cndmask_b32_e64 v68, v68, v108, s[86:87]
	v_cndmask_b32_e64 v69, v108, v69, s[86:87]
	v_cndmask_b32_e64 v72, v72, v109, s[86:87]
	v_cndmask_b32_e64 v73, v109, v73, s[86:87]
	v_cndmask_b32_e64 v76, v76, v110, s[86:87]
	v_cndmask_b32_e64 v77, v110, v77, s[86:87]
	v_cndmask_b32_e64 v80, v80, v111, s[86:87]
	v_cndmask_b32_e64 v81, v111, v81, s[86:87]
	v_cndmask_b32_e64 v70, v70, v112, s[86:87]
	v_cndmask_b32_e64 v71, v112, v71, s[86:87]
	v_cndmask_b32_e64 v74, v74, v113, s[86:87]
	v_cndmask_b32_e64 v75, v113, v75, s[86:87]
	v_cndmask_b32_e64 v78, v78, v114, s[86:87]
	v_cndmask_b32_e64 v79, v114, v79, s[86:87]
	v_cndmask_b32_e64 v82, v82, v115, s[86:87]
	v_cndmask_b32_e64 v83, v115, v83, s[86:87]
	v_cndmask_b32_e64 v100, v70, v68, s[88:89]
	v_cndmask_b32_e64 v101, v74, v72, s[88:89]
	v_cndmask_b32_e64 v102, v78, v76, s[88:89]
	v_cndmask_b32_e64 v103, v82, v80, s[88:89]
	v_cndmask_b32_e64 v104, v71, v69, s[88:89]
	v_cndmask_b32_e64 v105, v75, v73, s[88:89]
	v_cndmask_b32_e64 v106, v79, v77, s[88:89]
	v_cndmask_b32_e64 v107, v83, v81, s[88:89]
	v_mov_b32_dpp v108, v100 quad_perm:[2,3,0,1] row_mask:0xf bank_mask:0xf
	v_mov_b32_dpp v109, v101 quad_perm:[2,3,0,1] row_mask:0xf bank_mask:0xf
	v_mov_b32_dpp v110, v102 quad_perm:[2,3,0,1] row_mask:0xf bank_mask:0xf
	v_mov_b32_dpp v111, v103 quad_perm:[2,3,0,1] row_mask:0xf bank_mask:0xf
	v_mov_b32_dpp v112, v104 quad_perm:[2,3,0,1] row_mask:0xf bank_mask:0xf
	v_mov_b32_dpp v113, v105 quad_perm:[2,3,0,1] row_mask:0xf bank_mask:0xf
	v_mov_b32_dpp v114, v106 quad_perm:[2,3,0,1] row_mask:0xf bank_mask:0xf
	v_mov_b32_dpp v115, v107 quad_perm:[2,3,0,1] row_mask:0xf bank_mask:0xf
	v_cndmask_b32_e64 v68, v68, v108, s[88:89]
	v_cndmask_b32_e64 v70, v108, v70, s[88:89]
	v_cndmask_b32_e64 v72, v72, v109, s[88:89]
	v_cndmask_b32_e64 v74, v109, v74, s[88:89]
	v_cndmask_b32_e64 v76, v76, v110, s[88:89]
	v_cndmask_b32_e64 v78, v110, v78, s[88:89]
	v_cndmask_b32_e64 v80, v80, v111, s[88:89]
	v_cndmask_b32_e64 v82, v111, v82, s[88:89]
	v_cndmask_b32_e64 v69, v69, v112, s[88:89]
	v_cndmask_b32_e64 v71, v112, v71, s[88:89]
	v_cndmask_b32_e64 v73, v73, v113, s[88:89]
	v_cndmask_b32_e64 v75, v113, v75, s[88:89]
	v_cndmask_b32_e64 v77, v77, v114, s[88:89]
	v_cndmask_b32_e64 v79, v114, v79, s[88:89]
	v_cndmask_b32_e64 v81, v81, v115, s[88:89]
	v_cndmask_b32_e64 v83, v115, v83, s[88:89]
	s_mov_b64 s[96:97], s[30:31]
	v_cvt_pk_bf16_f32 v100, v36, v37
	v_cvt_pk_bf16_f32 v101, v38, v39
	global_store_dwordx2 v91, v[100:101], s[96:97]
	v_cvt_pk_bf16_f32 v102, v68, v69
	v_cvt_pk_bf16_f32 v103, v70, v71
	global_store_dwordx2 v91, v[102:103], s[96:97] offset:32
	s_add_u32 s96, s96, 0x1080
	s_addc_u32 s97, s97, 0
	v_cvt_pk_bf16_f32 v100, v40, v41
	v_cvt_pk_bf16_f32 v101, v42, v43
	global_store_dwordx2 v91, v[100:101], s[96:97]
	v_cvt_pk_bf16_f32 v102, v72, v73
	v_cvt_pk_bf16_f32 v103, v74, v75
	global_store_dwordx2 v91, v[102:103], s[96:97] offset:32
	s_add_u32 s96, s96, 0x1080
	s_addc_u32 s97, s97, 0
	v_cvt_pk_bf16_f32 v100, v44, v45
	v_cvt_pk_bf16_f32 v101, v46, v47
	global_store_dwordx2 v91, v[100:101], s[96:97]
	v_cvt_pk_bf16_f32 v102, v76, v77
	v_cvt_pk_bf16_f32 v103, v78, v79
	global_store_dwordx2 v91, v[102:103], s[96:97] offset:32
	s_add_u32 s96, s96, 0x1080
	s_addc_u32 s97, s97, 0
	v_cvt_pk_bf16_f32 v100, v48, v49
	v_cvt_pk_bf16_f32 v101, v50, v51
	global_store_dwordx2 v91, v[100:101], s[96:97]
	v_cvt_pk_bf16_f32 v102, v80, v81
	v_cvt_pk_bf16_f32 v103, v82, v83
	global_store_dwordx2 v91, v[102:103], s[96:97] offset:32
	s_waitcnt vmcnt(8)
	s_branch .LBB0_663
